# attention loop, first half block: V tile written after the block-boundary barrier, the barrier in front of the K/V LDS writes removed (3 barriers per 2 KV blocks)
# baseline (speedup 1.0000x reference)
.LBB0_453:
	ds_read_b128 v[66:69], v209 offset:49152
	ds_read_b128 v[70:73], v209 offset:57344
	ds_read_b128 v[232:235], v214 offset:49152
	ds_read_b128 v[236:239], v214 offset:57344
	ds_read_b128 v[200:203], v213 offset:49152
	ds_read_b128 v[204:207], v213 offset:57344
	v_add_f32_e32 v164, 0, v165
	v_add_f32_e32 v164, v179, v164
	s_waitcnt lgkmcnt(5)
	v_mfma_f32_32x32x16_bf16 v[82:97], v[66:69], v[120:123], 0
	v_add_f32_e32 v164, v166, v164
	v_add_f32_e32 v164, v221, v164
	v_add_f32_e32 v164, v178, v164
	v_add_f32_e32 v164, v231, v164
	v_add_f32_e32 v164, v167, v164
	v_add_f32_e32 v164, v177, v164
	v_add_f32_e32 v164, v173, v164
	s_waitcnt lgkmcnt(4)
	v_mfma_f32_32x32x16_bf16 v[66:81], v[70:73], v[120:123], 0
	v_add_f32_e32 v164, v175, v164
	v_add_f32_e32 v164, v174, v164
	v_add_f32_e32 v164, v176, v164
	v_exp_f32_e32 v162, v162
	v_add_f32_e32 v164, v169, v164
	v_exp_f32_e32 v163, v163
	v_add_f32_e32 v164, v171, v164
	s_waitcnt lgkmcnt(3)
	v_mfma_f32_32x32x16_bf16 v[82:97], v[232:235], v[112:115], v[82:97]
	v_exp_f32_e32 v160, v160
	v_add_f32_e32 v164, v170, v164
	v_exp_f32_e32 v161, v161
	v_add_f32_e32 v164, v172, v164
	v_exp_f32_e32 v156, v156
	v_add_f32_e32 v164, v162, v164
	v_exp_f32_e32 v157, v157
	s_waitcnt lgkmcnt(2)
	v_mfma_f32_32x32x16_bf16 v[66:81], v[236:239], v[112:115], v[66:81]
	ds_read_b128 v[232:235], v212 offset:49152
	ds_read_b128 v[236:239], v212 offset:57344
	v_add_f32_e32 v164, v163, v164
	v_exp_f32_e32 v152, v152
	v_add_f32_e32 v164, v160, v164
	v_exp_f32_e32 v153, v153
	v_add_f32_e32 v164, v161, v164
	v_exp_f32_e32 v150, v150
	s_waitcnt lgkmcnt(3)
	v_mfma_f32_32x32x16_bf16 v[82:97], v[200:203], v[128:131], v[82:97]
	v_add_f32_e32 v164, v156, v164
	v_exp_f32_e32 v151, v151
	v_add_f32_e32 v164, v157, v164
	v_exp_f32_e32 v158, v158
	v_add_f32_e32 v164, v152, v164
	v_exp_f32_e32 v159, v159
	v_add_f32_e32 v164, v153, v164
	s_waitcnt lgkmcnt(2)
	v_mfma_f32_32x32x16_bf16 v[66:81], v[204:207], v[128:131], v[66:81]
	ds_read_b128 v[200:203], v211 offset:49152
	ds_read_b128 v[204:207], v211 offset:57344
	v_exp_f32_e32 v154, v154
	v_add_f32_e32 v164, v150, v164
	v_exp_f32_e32 v155, v155
	v_add_f32_e32 v164, v151, v164
	v_exp_f32_e32 v148, v148
	v_add_f32_e32 v164, v158, v164
	s_waitcnt lgkmcnt(3)
	v_mfma_f32_32x32x16_bf16 v[82:97], v[232:235], v[124:127], v[82:97]
	v_exp_f32_e32 v149, v149
	v_add_f32_e32 v164, v159, v164
	v_add_f32_e32 v164, v154, v164
	v_add_f32_e32 v164, v155, v164
	v_add_f32_e32 v164, v148, v164
	v_add_f32_e32 v218, v149, v164
	v_mov_b32_e32 v219, v218
	s_waitcnt lgkmcnt(2)
	v_mfma_f32_32x32x16_bf16 v[66:81], v[236:239], v[124:127], v[66:81]
	ds_read_b128 v[232:235], v210 offset:49152
	ds_read_b128 v[236:239], v210 offset:57344
	v_permlane32_swap_b32_e32 v218, v219
	s_waitcnt lgkmcnt(3)
	v_mfma_f32_32x32x16_bf16 v[82:97], v[200:203], v[116:119], v[82:97]
	s_waitcnt lgkmcnt(2)
	v_mfma_f32_32x32x16_bf16 v[66:81], v[204:207], v[116:119], v[66:81]
	ds_read_b128 v[200:203], v216 offset:49152
	ds_read_b128 v[204:207], v216 offset:57344
	s_waitcnt lgkmcnt(3)
	v_mfma_f32_32x32x16_bf16 v[82:97], v[232:235], v[108:111], v[82:97]
	s_waitcnt lgkmcnt(2)
	v_mfma_f32_32x32x16_bf16 v[66:81], v[236:239], v[108:111], v[66:81]
	ds_read_b128 v[232:235], v215 offset:49152
	ds_read_b128 v[236:239], v215 offset:57344
	s_waitcnt lgkmcnt(3)
	v_mfma_f32_32x32x16_bf16 v[82:97], v[200:203], v[104:107], v[82:97]
	s_waitcnt lgkmcnt(2)
	v_mfma_f32_32x32x16_bf16 v[66:81], v[204:207], v[104:107], v[66:81]
	v_cvt_pk_bf16_f32 v164, v165, v179
	v_cvt_pk_bf16_f32 v165, v166, v221
	v_cvt_pk_bf16_f32 v166, v178, v231
	v_cvt_pk_bf16_f32 v167, v167, v177
	v_cvt_pk_bf16_f32 v220, v173, v175
	v_cvt_pk_bf16_f32 v221, v174, v176
	s_waitcnt lgkmcnt(1)
	v_mfma_f32_32x32x16_bf16 v[82:97], v[232:235], v[100:103], v[82:97]
	v_cvt_pk_bf16_f32 v222, v169, v171
	v_permlane32_swap_b32_e32 v164, v166
	v_cvt_pk_bf16_f32 v223, v170, v172
	v_permlane32_swap_b32_e32 v220, v222
	v_cvt_pk_bf16_f32 v170, v162, v163
	s_waitcnt lgkmcnt(0)
	v_mfma_f32_32x32x16_bf16 v[66:81], v[236:239], v[100:103], v[66:81]
	ds_read_b64_tr_b16 v[232:233], v192 offset:0
	ds_read_b64_tr_b16 v[234:235], v192 offset:0x800
	ds_read_b64_tr_b16 v[236:237], v192 offset:0x1000
	ds_read_b64_tr_b16 v[238:239], v192 offset:0x1800
	ds_read_b64_tr_b16 v[240:241], v192 offset:0x2000
	ds_read_b64_tr_b16 v[242:243], v192 offset:0x2800
	ds_read_b64_tr_b16 v[244:245], v192 offset:0x3000
	ds_read_b64_tr_b16 v[246:247], v192 offset:0x3800
	v_cvt_pk_bf16_f32 v171, v160, v161
	v_cvt_pk_bf16_f32 v172, v156, v157
	v_cvt_pk_bf16_f32 v173, v152, v153
	v_cvt_pk_bf16_f32 v174, v150, v151
	v_cvt_pk_bf16_f32 v175, v158, v159
	v_cvt_pk_bf16_f32 v176, v154, v155
	v_cvt_pk_bf16_f32 v177, v148, v149
	v_permlane32_swap_b32_e32 v165, v167
	v_permlane32_swap_b32_e32 v221, v223
	v_permlane32_swap_b32_e32 v170, v172
	v_permlane32_swap_b32_e32 v171, v173
	v_permlane32_swap_b32_e32 v174, v176
	v_permlane32_swap_b32_e32 v175, v177
	v_add_co_u32_e32 v148, vcc, s1, v180
	s_nop 1
	v_addc_co_u32_e32 v149, vcc, -1, v181, vcc
	v_add_co_u32_e32 v152, vcc, s28, v180
	s_nop 1
	v_addc_co_u32_e32 v153, vcc, -1, v181, vcc
	v_add_co_u32_e32 v156, vcc, s19, v180
	global_load_dwordx4 v[148:151], v[148:149], off
	s_nop 0
	global_load_dwordx4 v[152:155], v[152:153], off
	v_addc_co_u32_e32 v157, vcc, -1, v181, vcc
	v_add_co_u32_e32 v160, vcc, s27, v180
	s_nop 1
	v_addc_co_u32_e32 v161, vcc, -1, v181, vcc
	global_load_dwordx4 v[156:159], v[156:157], off
	s_nop 0
	global_load_dwordx4 v[160:163], v[160:161], off
	s_waitcnt lgkmcnt(0)
	s_nop 0
	v_mfma_f32_32x32x16_bf16 v[2:17], v[164:167], v[232:235], v[2:17]
	ds_read_b64_tr_b16 v[232:233], v192 offset:0x200
	ds_read_b64_tr_b16 v[234:235], v192 offset:0xa00
	v_mfma_f32_32x32x16_bf16 v[2:17], v[220:223], v[236:239], v[2:17]
	ds_read_b64_tr_b16 v[236:237], v192 offset:0x1200
	ds_read_b64_tr_b16 v[238:239], v192 offset:0x1a00
	v_mfma_f32_32x32x16_bf16 v[2:17], v[170:173], v[240:243], v[2:17]
	ds_read_b64_tr_b16 v[240:241], v192 offset:0x2200
	ds_read_b64_tr_b16 v[242:243], v192 offset:0x2a00
	v_mfma_f32_32x32x16_bf16 v[2:17], v[174:177], v[244:247], v[2:17]
	ds_read_b64_tr_b16 v[244:245], v192 offset:0x3200
	ds_read_b64_tr_b16 v[246:247], v192 offset:0x3a00
	s_waitcnt lgkmcnt(0)
	v_mfma_f32_32x32x16_bf16 v[50:65], v[164:167], v[232:235], v[50:65]
	ds_read_b64_tr_b16 v[232:233], v192 offset:0x400
	ds_read_b64_tr_b16 v[234:235], v192 offset:0xc00
	v_mfma_f32_32x32x16_bf16 v[50:65], v[220:223], v[236:239], v[50:65]
	ds_read_b64_tr_b16 v[236:237], v192 offset:0x1400
	ds_read_b64_tr_b16 v[238:239], v192 offset:0x1c00
	v_mfma_f32_32x32x16_bf16 v[50:65], v[170:173], v[240:243], v[50:65]
	ds_read_b64_tr_b16 v[240:241], v192 offset:0x2400
	ds_read_b64_tr_b16 v[242:243], v192 offset:0x2c00
	v_mfma_f32_32x32x16_bf16 v[50:65], v[174:177], v[244:247], v[50:65]
	ds_read_b64_tr_b16 v[244:245], v192 offset:0x3400
	ds_read_b64_tr_b16 v[246:247], v192 offset:0x3c00
	s_waitcnt lgkmcnt(0)
	v_mfma_f32_32x32x16_bf16 v[34:49], v[164:167], v[232:235], v[34:49]
	ds_read_b64_tr_b16 v[232:233], v192 offset:0x600
	ds_read_b64_tr_b16 v[234:235], v192 offset:0xe00
	v_mfma_f32_32x32x16_bf16 v[34:49], v[220:223], v[236:239], v[34:49]
	ds_read_b64_tr_b16 v[236:237], v192 offset:0x1600
	ds_read_b64_tr_b16 v[238:239], v192 offset:0x1e00
	v_mfma_f32_32x32x16_bf16 v[34:49], v[170:173], v[240:243], v[34:49]
	ds_read_b64_tr_b16 v[240:241], v192 offset:0x2600
	ds_read_b64_tr_b16 v[242:243], v192 offset:0x2e00
	v_mfma_f32_32x32x16_bf16 v[34:49], v[174:177], v[244:247], v[34:49]
	ds_read_b64_tr_b16 v[244:245], v192 offset:0x3600
	ds_read_b64_tr_b16 v[246:247], v192 offset:0x3e00
	s_waitcnt lgkmcnt(0)
	v_mfma_f32_32x32x16_bf16 v[18:33], v[164:167], v[232:235], v[18:33]
	v_max_f32_e32 v164, v83, v83
	v_max_f32_e32 v165, v82, v82
	v_max_f32_e32 v164, v165, v164
	v_max3_f32 v164, v164, v84, v85
	v_max3_f32 v164, v164, v86, v87
	v_max3_f32 v164, v164, v88, v89
	v_max3_f32 v164, v164, v90, v91
	v_max3_f32 v164, v164, v92, v93
	v_max3_f32 v164, v164, v94, v95
	v_mfma_f32_32x32x16_bf16 v[18:33], v[220:223], v[236:239], v[18:33]
	v_max3_f32 v164, v164, v96, v97
	v_max3_f32 v164, v164, v66, v67
	v_max3_f32 v164, v164, v68, v69
	v_max3_f32 v164, v164, v70, v71
	v_max3_f32 v164, v164, v72, v73
	v_max3_f32 v164, v164, v74, v75
	v_max3_f32 v164, v164, v76, v77
	v_max3_f32 v164, v164, v78, v79
	v_mfma_f32_32x32x16_bf16 v[18:33], v[170:173], v[240:243], v[18:33]
	v_max3_f32 v164, v164, v80, v81
	v_mov_b32_e32 v165, v164
	s_nop 1
	v_permlane32_swap_b32_e32 v164, v165
	v_max_f32_e32 v165, v165, v165
	v_max_f32_e32 v164, v164, v164
	v_max_f32_e32 v164, v164, v165
	v_sub_f32_e32 v165, v164, v168
	v_cmp_ge_f32_e32 vcc, s0, v165
	v_max_f32_e32 v165, v168, v168
	v_max_f32_e32 v164, v165, v164
	v_mfma_f32_32x32x16_bf16 v[18:33], v[174:177], v[244:247], v[18:33]
	v_sub_f32_e32 v165, v168, v164
	v_mul_f32_e32 v165, 0x3e0293ee, v165
	v_exp_f32_e32 v165, v165
	s_cmp_eq_u64 vcc, exec
	s_cselect_b64 s[42:43], -1, 0
	s_waitcnt vmcnt(4)
	v_cndmask_b32_e64 v220, v165, 1.0, s[42:43]
	v_cmp_gt_f32_e32 vcc, 1.0, v220
	s_waitcnt vmcnt(5)
	ds_write_b128 v193, v[136:139] offset:32768
	s_waitcnt vmcnt(4)
	ds_write_b128 v194, v[144:147] offset:32768
	s_cbranch_vccz .LBB0_457
	s_and_saveexec_b64 s[4:5], s[40:41]
	ds_write_b32 v189, v220 offset:128
	s_or_b64 exec, exec, s[4:5]
	s_waitcnt lgkmcnt(0)
	v_add_u32_e32 v165, v188, v98
	ds_read_b128 v[170:173], v165 offset:224
	ds_read_b128 v[174:177], v165 offset:192
	ds_read_b128 v[232:235], v165 offset:160
	ds_read_b128 v[236:239], v165 offset:128
	s_waitcnt lgkmcnt(3)
	v_pk_mul_f32 v[14:15], v[14:15], v[170:171]
	s_waitcnt lgkmcnt(2)
	v_pk_mul_f32 v[10:11], v[10:11], v[174:175]
	s_waitcnt lgkmcnt(1)
	v_pk_mul_f32 v[6:7], v[6:7], v[232:233]
	v_pk_mul_f32 v[16:17], v[16:17], v[172:173]
	v_pk_mul_f32 v[12:13], v[12:13], v[176:177]
	v_pk_mul_f32 v[8:9], v[8:9], v[234:235]
	s_waitcnt lgkmcnt(0)
	v_pk_mul_f32 v[4:5], v[4:5], v[238:239]
	v_pk_mul_f32 v[2:3], v[2:3], v[236:237]
	v_pk_mul_f32 v[62:63], v[62:63], v[170:171]
	v_pk_mul_f32 v[58:59], v[58:59], v[174:175]
	v_pk_mul_f32 v[54:55], v[54:55], v[232:233]
	v_pk_mul_f32 v[64:65], v[64:65], v[172:173]
	v_pk_mul_f32 v[60:61], v[60:61], v[176:177]
	v_pk_mul_f32 v[56:57], v[56:57], v[234:235]
	v_pk_mul_f32 v[52:53], v[52:53], v[238:239]
	v_pk_mul_f32 v[50:51], v[50:51], v[236:237]
	v_pk_mul_f32 v[46:47], v[46:47], v[170:171]
	v_pk_mul_f32 v[42:43], v[42:43], v[174:175]
	v_pk_mul_f32 v[38:39], v[38:39], v[232:233]
	v_pk_mul_f32 v[48:49], v[48:49], v[172:173]
	v_pk_mul_f32 v[44:45], v[44:45], v[176:177]
	v_pk_mul_f32 v[40:41], v[40:41], v[234:235]
	v_pk_mul_f32 v[36:37], v[36:37], v[238:239]
	v_pk_mul_f32 v[34:35], v[34:35], v[236:237]
	v_pk_mul_f32 v[30:31], v[30:31], v[170:171]
	v_pk_mul_f32 v[26:27], v[26:27], v[174:175]
	v_pk_mul_f32 v[22:23], v[22:23], v[232:233]
	v_pk_mul_f32 v[32:33], v[32:33], v[172:173]
	v_pk_mul_f32 v[28:29], v[28:29], v[176:177]
	v_pk_mul_f32 v[24:25], v[24:25], v[234:235]
	v_pk_mul_f32 v[20:21], v[20:21], v[238:239]
	v_pk_mul_f32 v[18:19], v[18:19], v[236:237]
.LBB0_457:
	v_cndmask_b32_e64 v221, v164, v168, s[42:43]
	v_mul_f32_e32 v222, 0xbe0293ee, v221
	v_fmamk_f32 v82, v82, 0x3e0293ee, v222
	v_fmamk_f32 v83, v83, 0x3e0293ee, v222
	v_fmamk_f32 v84, v84, 0x3e0293ee, v222
	v_fmamk_f32 v85, v85, 0x3e0293ee, v222
	v_fmamk_f32 v86, v86, 0x3e0293ee, v222
	v_fmamk_f32 v87, v87, 0x3e0293ee, v222
	v_fmamk_f32 v88, v88, 0x3e0293ee, v222
	v_fmamk_f32 v89, v89, 0x3e0293ee, v222
	v_fmamk_f32 v90, v90, 0x3e0293ee, v222
	v_fmamk_f32 v91, v91, 0x3e0293ee, v222
	v_fmamk_f32 v92, v92, 0x3e0293ee, v222
	v_fmamk_f32 v93, v93, 0x3e0293ee, v222
	v_fmamk_f32 v94, v94, 0x3e0293ee, v222
	v_fmamk_f32 v95, v95, 0x3e0293ee, v222
	v_fmamk_f32 v96, v96, 0x3e0293ee, v222
	v_fmamk_f32 v97, v97, 0x3e0293ee, v222
	v_exp_f32_e32 v164, v82
	v_exp_f32_e32 v179, v83
	v_exp_f32_e32 v165, v84
	v_exp_f32_e32 v178, v85
	v_exp_f32_e32 v166, v86
	v_exp_f32_e32 v177, v87
	v_exp_f32_e32 v167, v88
	v_exp_f32_e32 v176, v89
	v_exp_f32_e32 v168, v90
	v_exp_f32_e32 v175, v91
	v_exp_f32_e32 v169, v92
	v_exp_f32_e32 v174, v93
	v_exp_f32_e32 v170, v94
	v_exp_f32_e32 v173, v95
	v_exp_f32_e32 v171, v96
	v_exp_f32_e32 v172, v97
	v_fmamk_f32 v238, v66, 0x3e0293ee, v222
	v_fmamk_f32 v239, v67, 0x3e0293ee, v222
	v_fmamk_f32 v240, v68, 0x3e0293ee, v222
	v_fmamk_f32 v241, v69, 0x3e0293ee, v222
	v_fmamk_f32 v242, v70, 0x3e0293ee, v222
	v_fmamk_f32 v231, v71, 0x3e0293ee, v222
	v_fmamk_f32 v232, v72, 0x3e0293ee, v222
	v_fmamk_f32 v233, v73, 0x3e0293ee, v222
	v_fmamk_f32 v234, v74, 0x3e0293ee, v222
	v_fmamk_f32 v235, v75, 0x3e0293ee, v222
	v_fmamk_f32 v236, v76, 0x3e0293ee, v222
	v_fmamk_f32 v237, v77, 0x3e0293ee, v222
	v_fmamk_f32 v223, v78, 0x3e0293ee, v222
	v_fmamk_f32 v243, v79, 0x3e0293ee, v222
	v_fmamk_f32 v244, v80, 0x3e0293ee, v222
	v_fmac_f32_e32 v222, 0x3e0293ee, v81
	s_waitcnt lgkmcnt(0)
	s_barrier
	ds_write_b128 v195, v[132:135]
	ds_write_b128 v208, v[140:143]
	ds_read_b128 v[66:69], v209 offset:32768
	ds_read_b128 v[70:73], v209 offset:40960
	ds_read_b128 v[246:249], v214 offset:32768
	ds_read_b128 v[196:199], v214 offset:40960
	ds_read_b128 v[200:203], v213 offset:32768
	ds_read_b128 v[204:207], v213 offset:40960
	v_exp_f32_e32 v231, v231
	v_exp_f32_e32 v232, v232
	s_waitcnt lgkmcnt(5)
	v_mfma_f32_32x32x16_bf16 v[82:97], v[66:69], v[120:123], 0
	v_exp_f32_e32 v233, v233
	v_exp_f32_e32 v234, v234
	v_exp_f32_e32 v235, v235
	v_exp_f32_e32 v236, v236
	v_exp_f32_e32 v237, v237
	s_waitcnt lgkmcnt(4)
	v_mfma_f32_32x32x16_bf16 v[66:81], v[70:73], v[120:123], 0
	s_waitcnt lgkmcnt(3)
	v_mfma_f32_32x32x16_bf16 v[82:97], v[246:249], v[112:115], v[82:97]
	s_waitcnt lgkmcnt(2)
	v_mfma_f32_32x32x16_bf16 v[66:81], v[196:199], v[112:115], v[66:81]
	ds_read_b128 v[196:199], v212 offset:32768
	ds_read_b128 v[246:249], v212 offset:40960
	s_waitcnt lgkmcnt(3)
	v_mfma_f32_32x32x16_bf16 v[82:97], v[200:203], v[128:131], v[82:97]
	s_waitcnt lgkmcnt(2)
	v_mfma_f32_32x32x16_bf16 v[66:81], v[204:207], v[128:131], v[66:81]
	ds_read_b128 v[200:203], v211 offset:32768
	ds_read_b128 v[204:207], v211 offset:40960
	s_waitcnt lgkmcnt(3)
	v_mfma_f32_32x32x16_bf16 v[82:97], v[196:199], v[124:127], v[82:97]
	s_waitcnt lgkmcnt(2)
	v_mfma_f32_32x32x16_bf16 v[66:81], v[246:249], v[124:127], v[66:81]
	ds_read_b128 v[196:199], v210 offset:32768
	ds_read_b128 v[246:249], v210 offset:40960
	s_waitcnt lgkmcnt(3)
	v_mfma_f32_32x32x16_bf16 v[82:97], v[200:203], v[116:119], v[82:97]
	s_waitcnt lgkmcnt(2)
	v_mfma_f32_32x32x16_bf16 v[66:81], v[204:207], v[116:119], v[66:81]
	ds_read_b128 v[200:203], v216 offset:32768
	ds_read_b128 v[204:207], v216 offset:40960
	s_waitcnt lgkmcnt(3)
	v_mfma_f32_32x32x16_bf16 v[82:97], v[196:199], v[108:111], v[82:97]
	s_waitcnt lgkmcnt(2)
	v_mfma_f32_32x32x16_bf16 v[66:81], v[246:249], v[108:111], v[66:81]
	ds_read_b128 v[196:199], v215 offset:32768
	ds_read_b128 v[246:249], v215 offset:40960
	s_waitcnt lgkmcnt(3)
	v_mfma_f32_32x32x16_bf16 v[82:97], v[200:203], v[104:107], v[82:97]
	s_waitcnt lgkmcnt(2)
	v_mfma_f32_32x32x16_bf16 v[66:81], v[204:207], v[104:107], v[66:81]
	s_waitcnt lgkmcnt(1)
	v_mfma_f32_32x32x16_bf16 v[82:97], v[196:199], v[100:103], v[82:97]
	v_exp_f32_e32 v196, v238
	v_exp_f32_e32 v238, v242
	v_exp_f32_e32 v242, v222
	v_add_f32_e32 v222, 0, v164
	v_add_f32_e32 v222, v179, v222
	v_add_f32_e32 v222, v165, v222
	v_add_f32_e32 v222, v178, v222
	v_add_f32_e32 v222, v166, v222
	v_add_f32_e32 v222, v177, v222
	v_add_f32_e32 v222, v167, v222
	v_add_f32_e32 v222, v176, v222
	v_add_f32_e32 v222, v168, v222
	v_add_f32_e32 v222, v175, v222
	v_add_f32_e32 v222, v169, v222
	v_add_f32_e32 v222, v174, v222
	v_add_f32_e32 v222, v170, v222
	v_exp_f32_e32 v197, v239
	v_add_f32_e32 v222, v173, v222
	v_exp_f32_e32 v198, v240
	v_add_f32_e32 v222, v171, v222
	v_exp_f32_e32 v199, v241
	v_add_f32_e32 v222, v172, v222
	v_add_f32_e32 v222, v196, v222
	v_add_f32_e32 v222, v197, v222
	v_add_f32_e32 v222, v198, v222
	v_add_f32_e32 v222, v199, v222
	v_add_f32_e32 v222, v238, v222
	v_add_f32_e32 v222, v231, v222
	v_add_f32_e32 v222, v232, v222
	v_add_f32_e32 v222, v233, v222
	v_exp_f32_e32 v239, v223
	v_add_f32_e32 v222, v234, v222
	v_exp_f32_e32 v240, v243
	v_add_f32_e32 v222, v235, v222
	s_waitcnt lgkmcnt(0)
	v_mfma_f32_32x32x16_bf16 v[66:81], v[246:249], v[100:103], v[66:81]
	v_exp_f32_e32 v241, v244
	v_add_f32_e32 v222, v236, v222
	v_add_f32_e32 v222, v237, v222
	v_add_f32_e32 v222, v239, v222
	v_add_f32_e32 v222, v240, v222
	v_add_f32_e32 v222, v241, v222
	v_add_f32_e32 v222, v242, v222
	v_mov_b32_e32 v223, v222
	v_cvt_pk_bf16_f32 v164, v164, v179
	v_cvt_pk_bf16_f32 v165, v165, v178
	v_cvt_pk_bf16_f32 v166, v166, v177
	v_cvt_pk_bf16_f32 v167, v167, v176
	v_cvt_pk_bf16_f32 v168, v168, v175
	v_cvt_pk_bf16_f32 v169, v169, v174
	v_cvt_pk_bf16_f32 v170, v170, v173
	v_cvt_pk_bf16_f32 v171, v171, v172
	v_cvt_pk_bf16_f32 v172, v196, v197
	v_cvt_pk_bf16_f32 v173, v198, v199
	v_cvt_pk_bf16_f32 v174, v238, v231
	v_cvt_pk_bf16_f32 v175, v232, v233
	v_cvt_pk_bf16_f32 v176, v234, v235
	v_cvt_pk_bf16_f32 v177, v236, v237
	v_cvt_pk_bf16_f32 v178, v239, v240
	v_cvt_pk_bf16_f32 v179, v241, v242
	s_nop 1
	v_permlane32_swap_b32_e32 v222, v223
	v_permlane32_swap_b32_e32 v164, v166
	v_permlane32_swap_b32_e32 v165, v167
	v_permlane32_swap_b32_e32 v168, v170
	v_permlane32_swap_b32_e32 v169, v171
	v_permlane32_swap_b32_e32 v172, v174
	v_permlane32_swap_b32_e32 v173, v175
	v_permlane32_swap_b32_e32 v176, v178
	v_permlane32_swap_b32_e32 v177, v179
	s_cmp_gt_u32 s6, 64
	s_cselect_b64 s[4:5], -1, 0
	s_and_b64 vcc, exec, s[4:5]
	s_cbranch_vccnz .LBB0_459
	v_add_co_u32_e32 v132, vcc, 0xffffc000, v180
	s_nop 1
	v_addc_co_u32_e32 v133, vcc, -1, v181, vcc
	v_add_co_u32_e32 v136, vcc, 0xff77c000, v180
	s_nop 1
	v_addc_co_u32_e32 v137, vcc, -1, v181, vcc
	v_add_co_u32_e32 v144, vcc, 0xff780000, v180
	global_load_dwordx4 v[132:135], v[132:133], off
	s_nop 0
	global_load_dwordx4 v[136:139], v[136:137], off
	v_addc_co_u32_e32 v145, vcc, -1, v181, vcc
	global_load_dwordx4 v[140:143], v[180:181], off
	s_nop 0
	global_load_dwordx4 v[144:147], v[144:145], off
